# hg<false>: next-chunk loads via scalar base + invariant lane offsets (no per-chunk 64-bit VALU address math)
# speedup vs baseline: 1.0003x; 1.0003x over previous
; #define LAS __attribute__((address_space(3)))
; __device__ __forceinline__ unsigned pk2(float lo, float hi) { typedef float f2v __attribute__((ext_vector_type(2))); typedef __bf16 b2v __attribute__((ext_vector_type(2))); const f2v v = {lo, hi}; const b2v b = __builtin_convertvector(v, b2v); return __builtin_bit_cast(unsigned, b); }
; #define lane lane_id()
; template <bool FULL, bool STORE = true>
; __device__ __forceinline__ void hg_item(const Prm& P, LAS unsigned char* lds, int item, int wave) {
;     ...
;     f32x16 S[2];
; #pragma unroll
;     for (int i = 0; i < 2; ++i)
; #pragma unroll
;         for (int r = 0; r < 16; ++r) S[i][r] = 0.f;
;     float sumlog0 = 0.f, sumlog1 = 0.f;
;     if (FULL) {
;         for (int s2 = 0; s2 < seg; ++s2) { const int it2 = item - seg + s2;
; #pragma unroll
;             for (int g4 = 0; g4 < 4; ++g4) { const f32x4 d = *(const f32x4*)(DEC + it2 * 128 + kb * 32 + 8 * g4 + 4 * lh);
; #pragma unroll
;                 for (int i = 0; i < 2; ++i)
; #pragma unroll
;                     for (int j = 0; j < 4; ++j) { const int r = 4 * g4 + j; S[i][r] = d[j] * S[i][r] + AGG[(size_t)((it2 * 8 + wave) * 2 + i) * 1024 + r * 64 + lane]; } } }
; #pragma unroll
;         for (int i = 0; i < 2; ++i)
; #pragma unroll
;             for (int g4 = 0; g4 < 4; ++g4) { u32x2 w; w.x = pk2(S[i][4 * g4], S[i][4 * g4 + 1]); w.y = pk2(S[i][4 * g4 + 2], S[i][4 * g4 + 3]);
;                 *(LAS u32x2*)(lds + HL_ST + ((vb0 + i) * 32 + l31) * 272 + (kb * 32 + 8 * g4 + 4 * lh) * 2) = w; }
;         for (int e = tid; e < 32 * 16; e += NTHR) { const int t = e >> 4, c = e & 15; *(LAS unsigned*)(lds + HL_PP + t * 144 + 64 + c * 4) = 0u; }
;     }
;     float c0[8], c1[8]; unsigned qw[8], ivw[8]; u32x4 ghw0, ghw1;
;     ...
;     HG_LOADS(0);
.LBB0_700:
	s_lshl_b32 s36, s62, 1
	s_and_b32 s26, s60, 0x1c00
	s_and_b32 s67, s36, 0x700
	s_ashr_i32 s36, s65, 6
	s_lshl_b32 s66, s65, 10
	s_add_i32 s26, s33, s26
	s_ashr_i32 s37, s36, 31
	s_and_b32 s66, s66, 0x1c00
	s_lshl_b64 s[34:35], s[26:27], 11
	s_lshl_b64 s[38:39], s[36:37], 13
	s_add_i32 s66, s66, s33
	s_add_u32 s72, s38, s66
	v_mbcnt_lo_u32_b32 v36, -1, 0
	v_mbcnt_hi_u32_b32 v36, -1, v36
	s_addc_u32 s73, s39, 0
	v_lshlrev_b32_e32 v34, 1, v36
	s_lshl_b32 s66, s65, 4
	s_and_b32 s74, s66, 0x380
	s_mov_b32 s75, s27
	v_ashrrev_i32_e32 v35, 31, v34
	v_lshl_add_u64 v[38:39], v[34:35], 0, s[74:75]
	s_lshl_b64 s[72:73], s[72:73], 10
	v_lshl_add_u64 v[0:1], v[38:39], 0, s[72:73]
	v_lshlrev_b64 v[0:1], 1, v[0:1]
	v_lshl_add_u64 v[2:3], s[70:71], 0, v[0:1]
	s_mov_b64 s[72:73], 0x1000
	global_load_dword v16, v[2:3], off
	global_load_dword v17, v[2:3], off offset:2048
	v_lshl_add_u64 v[2:3], v[0:1], 0, s[72:73]
	v_lshl_add_u64 v[4:5], s[70:71], 0, v[2:3]
	s_mov_b64 s[72:73], 0x1800
	global_load_dword v18, v[4:5], off
	v_lshl_add_u64 v[4:5], v[0:1], 0, s[72:73]
	v_lshl_add_u64 v[6:7], s[70:71], 0, v[4:5]
	s_mov_b64 s[72:73], 0x2000
	global_load_dword v19, v[6:7], off
	v_lshl_add_u64 v[6:7], v[0:1], 0, s[72:73]
	v_lshl_add_u64 v[8:9], s[70:71], 0, v[6:7]
	s_mov_b64 s[72:73], 0x2800
	global_load_dword v20, v[8:9], off
	v_lshl_add_u64 v[8:9], v[0:1], 0, s[72:73]
	v_lshl_add_u64 v[10:11], s[70:71], 0, v[8:9]
	s_mov_b64 s[72:73], 0x3000
	global_load_dword v21, v[10:11], off
	v_lshl_add_u64 v[10:11], v[0:1], 0, s[72:73]
	v_lshl_add_u64 v[12:13], s[70:71], 0, v[10:11]
	s_mov_b64 s[72:73], 0x3800
	global_load_dword v22, v[12:13], off
	v_lshl_add_u64 v[12:13], v[0:1], 0, s[72:73]
	v_lshl_add_u64 v[14:15], s[70:71], 0, v[12:13]
	v_lshl_add_u64 v[0:1], s[24:25], 0, v[0:1]
	global_load_dword v14, v[14:15], off
	s_nop 0
	global_load_dword v37, v[0:1], off
	global_load_dword v65, v[0:1], off offset:2048
	v_lshl_add_u64 v[0:1], s[24:25], 0, v[2:3]
	v_lshl_add_u64 v[2:3], s[24:25], 0, v[4:5]
	v_lshl_add_u64 v[4:5], s[24:25], 0, v[6:7]
	v_lshl_add_u64 v[6:7], s[24:25], 0, v[8:9]
	v_lshl_add_u64 v[8:9], s[24:25], 0, v[10:11]
	v_lshl_add_u64 v[10:11], s[24:25], 0, v[12:13]
	global_load_dword v68, v[0:1], off
	global_load_dword v69, v[2:3], off
	global_load_dword v70, v[4:5], off
	global_load_dword v71, v[6:7], off
	global_load_dword v72, v[8:9], off
	global_load_dword v75, v[10:11], off
	s_add_u32 s38, s38, s26
	s_addc_u32 s39, s39, 0
	s_lshl_b64 s[38:39], s[38:39], 10
	s_add_u32 s26, s38, 0x10000
	v_and_b32_e32 v0, 31, v36
	s_movk_i32 s72, 0x120
	v_ashrrev_i32_e32 v1, 1, v36
	s_addc_u32 s38, s39, 0
	s_lshl_b64 s[36:37], s[36:37], 24
	v_mul_lo_u32 v66, v36, s72
	v_and_b32_e32 v67, -16, v1
	v_or_b32_e32 v1, s50, v0
	s_movk_i32 s72, 0x90
	s_add_u32 s34, s36, s34
	v_or_b32_e32 v0, s51, v0
	v_mul_lo_u32 v1, v1, s72
	s_addc_u32 s35, s37, s35
	s_or_b32 s34, s34, s67
	v_mul_u32_u24_e32 v3, 0x90, v0
	v_add_u32_e32 v4, 0, v1
	v_mov_b32_e32 v0, s34
	v_mov_b32_e32 v1, s35
	v_add_u32_e32 v2, s64, v67
	v_lshl_add_u64 v[0:1], v[34:35], 1, v[0:1]
	v_mov_b32_e32 v33, v32
	v_lshlrev_b32_e32 v64, 3, v36
	v_lshl_add_u64 v[42:43], s[28:29], 0, v[0:1]
	v_lshl_add_u64 v[44:45], s[30:31], 0, v[0:1]
	s_mov_b64 s[34:35], 0
	v_add_u32_e32 v73, v4, v67
	v_add_u32_e32 v74, v2, v3
	v_mov_b64_e32 v[40:41], v[32:33]
	v_mov_b32_e32 v23, v32
	v_mov_b32_e32 v24, v32
	v_mov_b32_e32 v25, v32
	v_mov_b32_e32 v26, v32
	v_mov_b32_e32 v27, v32
	v_mov_b32_e32 v28, v32
	v_mov_b32_e32 v29, v32
	v_mov_b32_e32 v30, v32
	v_mov_b32_e32 v31, v32
	v_mov_b32_e32 v0, 0
	v_mov_b32_e32 v1, v32
	v_mov_b32_e32 v2, v32
	v_mov_b32_e32 v3, v32
	v_mov_b32_e32 v4, v32
	s_waitcnt vmcnt(0)
	v_cvt_f32_f16_e32 v46, v16
	v_cvt_f32_f16_sdwa v47, v16 dst_sel:DWORD dst_unused:UNUSED_PAD src0_sel:WORD_1
	v_cvt_f32_f16_e32 v48, v17
	v_cvt_f32_f16_sdwa v49, v17 dst_sel:DWORD dst_unused:UNUSED_PAD src0_sel:WORD_1
	v_mov_b32_e32 v16, 0
	v_cvt_f32_f16_e32 v50, v18
	v_cvt_f32_f16_sdwa v51, v18 dst_sel:DWORD dst_unused:UNUSED_PAD src0_sel:WORD_1
	v_mov_b32_e32 v17, v32
	v_mov_b32_e32 v18, v32
	v_cvt_f32_f16_e32 v52, v19
	v_cvt_f32_f16_sdwa v53, v19 dst_sel:DWORD dst_unused:UNUSED_PAD src0_sel:WORD_1
	v_mov_b32_e32 v19, v32
	v_mov_b32_e32 v5, v32
	v_cvt_f32_f16_e32 v54, v20
	v_cvt_f32_f16_sdwa v55, v20 dst_sel:DWORD dst_unused:UNUSED_PAD src0_sel:WORD_1
	v_mov_b32_e32 v20, v32
	v_mov_b32_e32 v6, v32
	v_cvt_f32_f16_e32 v56, v21
	v_cvt_f32_f16_sdwa v57, v21 dst_sel:DWORD dst_unused:UNUSED_PAD src0_sel:WORD_1
	v_mov_b32_e32 v21, v32
	v_mov_b32_e32 v7, v32
	v_cvt_f32_f16_e32 v58, v22
	v_cvt_f32_f16_sdwa v59, v22 dst_sel:DWORD dst_unused:UNUSED_PAD src0_sel:WORD_1
	v_mov_b32_e32 v22, v32
	v_mov_b32_e32 v8, v32
	v_cvt_f32_f16_e32 v60, v14
	v_cvt_f32_f16_sdwa v61, v14 dst_sel:DWORD dst_unused:UNUSED_PAD src0_sel:WORD_1
	v_mov_b32_e32 v9, v32
	v_mov_b32_e32 v10, v32
	v_mov_b32_e32 v11, v32
	v_mov_b32_e32 v12, v32
	v_mov_b32_e32 v13, v32
	v_mov_b32_e32 v14, v32
	v_mov_b32_e32 v15, v32
	v_mov_b32_e32 v116, 0
	v_mov_b32_e32 v117, 0
	v_mov_b32_e32 v118, 0
	v_mov_b32_e32 v119, 0
	v_mov_b32_e32 v120, 0
	v_mov_b32_e32 v121, 0
	v_mov_b32_e32 v122, 0
	v_mov_b32_e32 v123, 0
	v_mov_b32_e32 v132, 0
	v_mov_b32_e32 v133, 0
	v_mov_b32_e32 v134, 0
	v_mov_b32_e32 v135, 0
	v_mov_b32_e32 v136, 0
	v_mov_b32_e32 v137, 0
	v_mov_b32_e32 v138, 0
	v_mov_b32_e32 v139, 0
	v_mov_b32_e32 v148, 0
	v_mov_b32_e32 v149, 0
	v_mov_b32_e32 v150, 0
	v_mov_b32_e32 v151, 0
	v_mov_b32_e32 v152, 0
	v_mov_b32_e32 v153, 0
	v_mov_b32_e32 v154, 0
	v_mov_b32_e32 v155, 0
	v_lshlrev_b32_e32 v172, 1, v38
	v_add_u32_e32 v173, 0x1000, v172
	v_add_u32_e32 v174, 0x2000, v172
	v_add_u32_e32 v175, 0x3000, v172
	s_branch .LBB0_702

; #define LAS __attribute__((address_space(3)))
; template <bool FULL, bool STORE = true>
; __device__ __forceinline__ void hg_item(const Prm& P, LAS unsigned char* lds, int item, int wave) {
;     ...
;         for (int ks = 0; ks < 4; ++ks) { const bf16x8 a = *(const LAS bf16x8*)(lds + HL_KDT + (kb * 32 + l31) * 144 + ks * 32 + lh * 16);
; #pragma unroll
;             for (int i = 0; i < 2; ++i) { const bf16x8 bb = *(const LAS bf16x8*)(lds + HL_IVT + ((vb0 + i) * 32 + l31) * 144 + ks * 32 + lh * 16); S[i] = __builtin_amdgcn_mfma_f32_32x32x16_bf16(a, bb, S[i], 0, 0, 0); } }
.LBB0_702:
	s_cmp_eq_u32 s34, 0x1e0000
	s_cbranch_scc1 .Lmy_hgf_skipl
	s_mov_b32 s36, s26
	s_mov_b32 s37, s38
	s_lshl_b64 s[36:37], s[36:37], 1
	s_add_u32 s78, s70, s36
	s_addc_u32 s79, s71, s37
	s_add_u32 s98, s24, s36
	s_addc_u32 s99, s25, s37
	global_load_dword v240, v172, s[78:79]
	global_load_dword v232, v172, s[98:99]
	global_load_dword v241, v172, s[78:79] offset:2048
	global_load_dword v233, v172, s[98:99] offset:2048
	v_mfma_f32_32x32x16_bf16 v[16:31], v[116:119], v[132:135], v[16:31]
	global_load_dword v242, v173, s[78:79]
	global_load_dword v234, v173, s[98:99]
	global_load_dword v243, v173, s[78:79] offset:2048
	global_load_dword v235, v173, s[98:99] offset:2048
	v_mfma_f32_32x32x16_bf16 v[0:15], v[116:119], v[148:151], v[0:15]
	global_load_dword v244, v174, s[78:79]
	global_load_dword v236, v174, s[98:99]
	global_load_dword v245, v174, s[78:79] offset:2048
	global_load_dword v237, v174, s[98:99] offset:2048
	v_mfma_f32_32x32x16_bf16 v[16:31], v[120:123], v[136:139], v[16:31]
	global_load_dword v246, v175, s[78:79]
	global_load_dword v238, v175, s[98:99]
	global_load_dword v247, v175, s[78:79] offset:2048
	global_load_dword v239, v175, s[98:99] offset:2048
	v_mfma_f32_32x32x16_bf16 v[0:15], v[120:123], v[152:155], v[0:15]
